# P5 static s_setprio 1 for waves 0-3 (leading half) before the attention loop, reset at exit
# speedup vs baseline: 1.0014x; 1.0014x over previous
; #define SBAR() __builtin_amdgcn_sched_barrier(0)
; #define VMW() asm volatile("s_waitcnt vmcnt(0)" ::: "memory")
; #define SLOAD_H(Kp, Vp, k0) do { S.st_v0 = load8(ROW(Vp, k0, sr)); S.st_v1 = load8(ROW(Vp, k0, 32 + sr));              \
;                          S.st_k0 = load8(ROW(Kp, k0, sr)); S.st_k1 = load8(ROW(Kp, k0, 32 + sr)); } while (0)
; #define SWRITE_HV(bf) do { *(bf16x8*)(V_lds + (bf) * SHM_V + vst0) = S.st_v0; *(bf16x8*)(V_lds + (bf) * SHM_V + vst1) = S.st_v1; } while (0)
; #define SWRITE_H(bf) do { SWRITE_HV(bf); SWRITE_HK(bf); } while (0)
; #define MASKT(P0_, P1_) sel_mask_tile(P0_, P1_, mw.x, mw.y, hi)
; template <int KB>
; __device__ __forceinline__ void qkt(f32x16& p0, f32x16& p1, const char* K_lds, int r32, int hi, const bf16x8* qr) {
;     p0 = f32x16{}; p1 = f32x16{};
;     const char* kb[4];
; #pragma unroll
;     for (int dd = 0; dd < 4; ++dd) kb[dd] = K_lds + KB * SHM_K + KSWZ(r32, (dd * 16 + hi * 8) * 2);
; #pragma unroll
;     for (int d0 = 0; d0 < 8; ++d0) { const char* a = kb[d0 & 3] + (d0 >> 2) * 128;
;         bf16x8 b0 = *reinterpret_cast<const bf16x8*>(a);
;         bf16x8 b1 = *reinterpret_cast<const bf16x8*>(a + 32 * 256);
;         p0 = __builtin_amdgcn_mfma_f32_32x32x16_bf16(b0, qr[d0], p0, 0, 0, 0);
;         p1 = __builtin_amdgcn_mfma_f32_32x32x16_bf16(b1, qr[d0], p1, 0, 0, 0); }
; __device__ __forceinline__ void attn_block(const BlockRef& cur, const BlockRef& nxt, char* lds, Seam& S) {
;     ...
;     SWRITE_HV(0); SBAR();
;     mw = LDMASK(0);
;     if (NT > 1) { SLOAD_H(Kh, Vh, KBASE(1)); }
;     SBAR(); qkt<0>(pA0, pA1, K_lds, r32, hi, S.qr);
;     MASKT(pA0, pA1); partialSM(pA0, pA1, m_reg, mnA, alA);
;     if (NT > 1) { VMW(); SWRITE_H(1); }
;     __syncthreads();
.LBB0_1298:
	v_readfirstlane_b32 s83, v0
	s_lshr_b32 s12, s38, 6
	s_or_b32 s81, s12, 3
	s_and_b32 s12, s83, 0x3fffffc0
	s_lshl_b32 s12, s12, 2
	s_add_i32 s84, s12, 0
	s_lshr_b32 s12, s83, 1
	s_and_b32 s12, s12, 0x7fffffe0
	v_and_b32_e32 v88, 31, v0
	v_or_b32_e32 v186, s12, v88
	s_mov_b32 s82, 1
	v_lshlrev_b32_e32 v165, 9, v186
	s_add_i32 s84, s84, 0x10000
	s_waitcnt vmcnt(1)
	ds_write_b128 v197, v[130:133]
	s_waitcnt vmcnt(0)
	ds_write_b128 v198, v[134:137]
	v_mov_b32_e32 v183, v167
	v_lshl_add_u64 v[2:3], s[70:71], 0, v[182:183]
	v_mov_b32_e32 v177, v167
	v_mov_b32_e32 v185, v167
	v_lshl_add_u64 v[2:3], v[2:3], 0, v[176:177]
	v_lshl_add_u64 v[4:5], s[70:71], 0, v[184:185]
	global_load_dwordx2 v[86:87], v165, s[68:69]
	v_lshl_add_u64 v[4:5], v[4:5], 0, v[176:177]
	global_load_dwordx4 v[50:53], v[2:3], off
	global_load_dwordx4 v[54:57], v[4:5], off
	v_lshl_add_u64 v[2:3], s[6:7], 0, v[182:183]
	v_lshl_add_u64 v[2:3], v[2:3], 0, v[176:177]
	v_lshl_add_u64 v[4:5], s[6:7], 0, v[184:185]
	v_lshl_add_u64 v[4:5], v[4:5], 0, v[176:177]
	global_load_dwordx4 v[58:61], v[2:3], off
	global_load_dwordx4 v[62:65], v[4:5], off
	ds_read_b128 v[2:5], v199 offset:32768
	ds_read_b128 v[6:9], v199 offset:32896
	s_mov_b32 s36, s13
	s_mov_b32 s37, s13
	s_mov_b32 s38, s13
	s_waitcnt lgkmcnt(1)
	v_mfma_f32_32x32x16_bf16 v[34:49], v[2:5], v[126:129], 0
	ds_read_b128 v[2:5], v199 offset:40960
	ds_read_b128 v[10:13], v199 offset:41088
	s_mov_b32 s39, s13
	s_mov_b32 s40, s13
	s_mov_b32 s41, s13
	s_mov_b32 s42, s13
	s_mov_b32 s43, s13
	s_mov_b32 s44, s13
	s_waitcnt lgkmcnt(1)
	v_mfma_f32_32x32x16_bf16 v[18:33], v[2:5], v[126:129], 0
	ds_read_b128 v[2:5], v200 offset:32768
	ds_read_b128 v[14:17], v200 offset:32896
	s_mov_b32 s45, s13
	s_mov_b32 s46, s13
	s_mov_b32 s47, s13
	s_mov_b32 s48, s13
	s_mov_b32 s49, s13
	s_mov_b32 s50, s13
	s_waitcnt lgkmcnt(1)
	v_mfma_f32_32x32x16_bf16 v[34:49], v[2:5], v[122:125], v[34:49]
	ds_read_b128 v[2:5], v200 offset:40960
	ds_read_b128 v[66:69], v200 offset:41088
	s_mov_b32 s51, s13
	v_lshl_add_u32 v185, v88, 2, s84
	v_lshl_add_u32 v183, v163, 2, s84
	v_add_u32_e32 v188, v170, v252
	s_mov_b64 s[16:17], s[70:71]
	s_mov_b64 s[100:101], s[6:7]
	v_mov_b32_e32 v205, 0
	s_waitcnt lgkmcnt(1)
	v_mfma_f32_32x32x16_bf16 v[18:33], v[2:5], v[122:125], v[18:33]
	ds_read_b128 v[2:5], v201 offset:32768
	ds_read_b128 v[70:73], v201 offset:32896
	s_waitcnt lgkmcnt(1)
	v_mfma_f32_32x32x16_bf16 v[34:49], v[2:5], v[118:121], v[34:49]
	ds_read_b128 v[2:5], v201 offset:40960
	ds_read_b128 v[74:77], v201 offset:41088
	s_waitcnt lgkmcnt(1)
	v_mfma_f32_32x32x16_bf16 v[18:33], v[2:5], v[118:121], v[18:33]
	ds_read_b128 v[2:5], v202 offset:32768
	ds_read_b128 v[78:81], v202 offset:32896
	s_waitcnt lgkmcnt(1)
	v_mfma_f32_32x32x16_bf16 v[34:49], v[2:5], v[114:117], v[34:49]
	ds_read_b128 v[2:5], v202 offset:40960
	ds_read_b128 v[82:85], v202 offset:41088
	s_waitcnt vmcnt(0)
	s_waitcnt vmcnt(3)
	ds_write_b128 v197, v[50:53] offset:16384
	s_waitcnt vmcnt(2)
	ds_write_b128 v198, v[54:57] offset:16384
	s_waitcnt vmcnt(1)
	ds_write_b128 v204, v[58:61] offset:49152
	s_waitcnt vmcnt(0)
	ds_write_b128 v204, v[62:65] offset:57344
	s_waitcnt lgkmcnt(0)
	s_barrier
	v_mfma_f32_32x32x16_bf16 v[34:49], v[6:9], v[110:113], v[34:49]
	v_mfma_f32_32x32x16_bf16 v[18:33], v[2:5], v[114:117], v[18:33]
	v_mfma_f32_32x32x16_bf16 v[34:49], v[14:17], v[106:109], v[34:49]
	v_mfma_f32_32x32x16_bf16 v[18:33], v[10:13], v[110:113], v[18:33]
	v_mov_b64_e32 v[2:3], s[36:37]
	v_mov_b64_e32 v[4:5], s[38:39]
	v_mov_b64_e32 v[6:7], s[40:41]
	v_mov_b64_e32 v[8:9], s[42:43]
	v_mov_b64_e32 v[10:11], s[44:45]
	v_mov_b64_e32 v[12:13], s[46:47]
	v_mov_b64_e32 v[14:15], s[48:49]
	v_mfma_f32_32x32x16_bf16 v[34:49], v[70:73], v[102:105], v[34:49]
	v_mov_b64_e32 v[16:17], s[50:51]
	v_mov_b64_e32 v[64:65], v[16:17]
	v_mov_b64_e32 v[62:63], v[14:15]
	v_mov_b64_e32 v[60:61], v[12:13]
	v_mov_b64_e32 v[58:59], v[10:11]
	v_mov_b64_e32 v[56:57], v[8:9]
	v_mov_b64_e32 v[54:55], v[6:7]
	v_mfma_f32_32x32x16_bf16 v[18:33], v[66:69], v[106:109], v[18:33]
	v_lshrrev_b32_e32 v66, v163, v86
	v_bfe_i32 v68, v66, 0, 1
	v_lshrrev_b32_e32 v67, v163, v87
	v_bfe_i32 v69, v67, 0, 1
	v_bfe_i32 v70, v67, 2, 1
	v_bfe_i32 v71, v67, 3, 1
	v_bfe_i32 v72, v67, 8, 1
	v_mfma_f32_32x32x16_bf16 v[34:49], v[78:81], v[98:101], v[34:49]
	v_bfe_i32 v73, v67, 9, 1
	v_bfe_i32 v78, v67, 18, 1
	v_bfe_i32 v79, v67, 19, 1
	v_bfe_i32 v80, v67, 24, 1
	v_bfe_i32 v81, v67, 25, 1
	v_mov_b64_e32 v[52:53], v[4:5]
	v_mov_b64_e32 v[50:51], v[2:3]
	v_mfma_f32_32x32x16_bf16 v[18:33], v[74:77], v[102:105], v[18:33]
	s_nop 3
	v_bitop3_b32 v68, v34, s74, v68 bitop3:0xe4
	v_bfe_i32 v34, v66, 1, 1
	v_bitop3_b32 v35, v35, s74, v34 bitop3:0xe4
	v_bfe_i32 v34, v66, 2, 1
	v_bitop3_b32 v36, v36, s74, v34 bitop3:0xe4
	v_bfe_i32 v34, v66, 3, 1
	v_bitop3_b32 v37, v37, s74, v34 bitop3:0xe4
	v_bfe_i32 v34, v66, 8, 1
	v_bitop3_b32 v38, v38, s74, v34 bitop3:0xe4
	v_bfe_i32 v34, v66, 9, 1
	v_bitop3_b32 v39, v39, s74, v34 bitop3:0xe4
	v_bfe_i32 v34, v66, 10, 1
	v_bitop3_b32 v40, v40, s74, v34 bitop3:0xe4
	v_bfe_i32 v34, v66, 11, 1
	v_mfma_f32_32x32x16_bf16 v[18:33], v[82:85], v[98:101], v[18:33]
; __device__ __forceinline__ void partialSM(f32x16& p0, f32x16& p1, float& m_reg, float& mn, float& alpha) {
;     float pmax = p0[0];
; #pragma unroll
;     for (int r = 1; r < 16; ++r) pmax = fmaxf(pmax, p0[r]);
; #pragma unroll
;     for (int r = 0; r < 16; ++r) pmax = fmaxf(pmax, p1[r]);
;     { auto rr = __builtin_amdgcn_permlane32_swap(__float_as_uint(pmax), __float_as_uint(pmax), false, false);
;       pmax = fmaxf(__uint_as_float(rr[0]), __uint_as_float(rr[1])); }
;     constexpr float C2 = 1.4426950408889634f * SCALE;
;     if (__builtin_expect(__all((pmax - m_reg) * SCALE <= THR), 1)) { mn = m_reg; alpha = 1.f; }
;     else { mn = fmaxf(m_reg, pmax); alpha = __builtin_amdgcn_exp2f((m_reg - mn) * C2); m_reg = mn; }
;     const float mnL = -mn * C2;
; #pragma unroll
;     for (int r = 0; r < 16; ++r) p0[r] = fmaf(p0[r], C2, mnL);
; #pragma unroll
;     for (int r = 0; r < 16; ++r) p1[r] = fmaf(p1[r], C2, mnL);
; #pragma unroll
;     for (int r = 0; r < 16; ++r) p0[r] = __builtin_amdgcn_exp2f(p0[r]);
	v_bitop3_b32 v41, v41, s74, v34 bitop3:0xe4
	v_bfe_i32 v34, v66, 16, 1
	v_bitop3_b32 v42, v42, s74, v34 bitop3:0xe4
	v_bfe_i32 v34, v66, 17, 1
	v_bitop3_b32 v43, v43, s74, v34 bitop3:0xe4
	v_bfe_i32 v34, v66, 18, 1
	v_bitop3_b32 v44, v44, s74, v34 bitop3:0xe4
	v_bfe_i32 v34, v66, 19, 1
	v_bitop3_b32 v45, v45, s74, v34 bitop3:0xe4
	v_bfe_i32 v34, v66, 24, 1
	v_bitop3_b32 v46, v46, s74, v34 bitop3:0xe4
	v_bfe_i32 v34, v66, 25, 1
	v_bitop3_b32 v47, v47, s74, v34 bitop3:0xe4
	v_bfe_i32 v34, v66, 26, 1
	v_bitop3_b32 v48, v48, s74, v34 bitop3:0xe4
	v_bfe_i32 v34, v66, 27, 1
	v_bitop3_b32 v18, v18, s74, v69 bitop3:0xe4
	v_bfe_i32 v69, v67, 1, 1
	v_bfe_i32 v74, v67, 10, 1
	v_bfe_i32 v75, v67, 11, 1
	v_bfe_i32 v76, v67, 16, 1
	v_bfe_i32 v77, v67, 17, 1
	v_bfe_i32 v82, v67, 26, 1
	v_bfe_i32 v66, v67, 27, 1
	v_bitop3_b32 v49, v49, s74, v34 bitop3:0xe4
	v_max_f32_e32 v34, v35, v35
	v_max_f32_e32 v67, v68, v68
	v_max_f32_e32 v34, v67, v34
	v_max3_f32 v34, v34, v36, v37
	v_max3_f32 v34, v34, v38, v39
	v_max3_f32 v34, v34, v40, v41
	v_max3_f32 v34, v34, v42, v43
	v_max3_f32 v34, v34, v44, v45
	v_max3_f32 v34, v34, v46, v47
	v_max3_f32 v34, v34, v48, v49
	v_bitop3_b32 v19, v19, s74, v69 bitop3:0xe4
	v_bitop3_b32 v20, v20, s74, v70 bitop3:0xe4
	v_max3_f32 v34, v34, v18, v19
	v_bitop3_b32 v21, v21, s74, v71 bitop3:0xe4
	v_bitop3_b32 v22, v22, s74, v72 bitop3:0xe4
	v_max3_f32 v34, v34, v20, v21
	v_bitop3_b32 v23, v23, s74, v73 bitop3:0xe4
	v_bitop3_b32 v24, v24, s74, v74 bitop3:0xe4
	v_max3_f32 v34, v34, v22, v23
	v_bitop3_b32 v25, v25, s74, v75 bitop3:0xe4
	v_bitop3_b32 v26, v26, s74, v76 bitop3:0xe4
	v_max3_f32 v34, v34, v24, v25
	v_bitop3_b32 v27, v27, s74, v77 bitop3:0xe4
	v_bitop3_b32 v28, v28, s74, v78 bitop3:0xe4
	v_max3_f32 v34, v34, v26, v27
	v_bitop3_b32 v29, v29, s74, v79 bitop3:0xe4
	v_bitop3_b32 v30, v30, s74, v80 bitop3:0xe4
	v_max3_f32 v34, v34, v28, v29
	v_bitop3_b32 v31, v31, s74, v81 bitop3:0xe4
	v_bitop3_b32 v32, v32, s74, v82 bitop3:0xe4
	v_max3_f32 v34, v34, v30, v31
	v_bitop3_b32 v33, v33, s74, v66 bitop3:0xe4
	v_max3_f32 v34, v34, v32, v33
	v_mov_b32_e32 v66, v34
	s_nop 1
	v_permlane32_swap_b32_e32 v34, v66
	v_max_f32_e32 v66, v66, v66
	v_max_f32_e32 v34, v34, v34
	v_max_f32_e32 v34, v34, v66
	v_add_f32_e32 v66, 0x7149f2ca, v34
	v_mul_f32_e32 v66, 0x3db504f3, v66
	v_max_f32_e32 v34, 0xf149f2ca, v34
	v_cmp_ge_f32_e32 vcc, s75, v66
	v_sub_f32_e32 v66, 0xf149f2ca, v34
	v_mul_f32_e32 v66, 0x3e0293ee, v66
	s_cmp_eq_u64 vcc, exec
	v_exp_f32_e32 v66, v66
	s_cselect_b64 vcc, -1, 0
	v_cndmask_b32_e32 v206, v34, v203, vcc
	v_mul_f32_e32 v34, 0xbe0293ee, v206
	v_mov_b32_e32 v67, v34
	v_cndmask_b32_e64 v177, v66, 1.0, vcc
	v_fmamk_f32 v66, v68, 0x3e0293ee, v34
	v_fmamk_f32 v35, v35, 0x3e0293ee, v34
	v_fmamk_f32 v36, v36, 0x3e0293ee, v34
	v_fmamk_f32 v37, v37, 0x3e0293ee, v34
	v_fmamk_f32 v38, v38, 0x3e0293ee, v34
	v_fmamk_f32 v39, v39, 0x3e0293ee, v34
	v_fmamk_f32 v40, v40, 0x3e0293ee, v34
	v_fmamk_f32 v41, v41, 0x3e0293ee, v34
	v_fmamk_f32 v42, v42, 0x3e0293ee, v34
	v_fmamk_f32 v43, v43, 0x3e0293ee, v34
	v_fmamk_f32 v44, v44, 0x3e0293ee, v34
	v_fmamk_f32 v45, v45, 0x3e0293ee, v34
	v_fmamk_f32 v46, v46, 0x3e0293ee, v34
	v_fmamk_f32 v47, v47, 0x3e0293ee, v34
	v_fmamk_f32 v48, v48, 0x3e0293ee, v34
	v_fmac_f32_e32 v67, 0x3e0293ee, v49
	v_exp_f32_e32 v219, v66
	v_exp_f32_e32 v220, v35
	v_exp_f32_e32 v221, v36
	v_exp_f32_e32 v222, v37
	v_exp_f32_e32 v223, v38
	v_exp_f32_e32 v225, v39
	v_exp_f32_e32 v224, v40
	v_exp_f32_e32 v226, v41
	v_exp_f32_e32 v211, v42
	v_exp_f32_e32 v212, v43
	v_exp_f32_e32 v213, v44
	v_exp_f32_e32 v215, v45
	v_exp_f32_e32 v214, v46
	v_exp_f32_e32 v216, v47
	v_exp_f32_e32 v217, v48
	v_exp_f32_e32 v218, v67
	s_lshl_b32 s36, s83, 8
	v_pk_fma_f32 v[152:153], v[32:33], s[14:15], v[34:35] op_sel_hi:[1,0,0]
	v_pk_fma_f32 v[156:157], v[30:31], s[14:15], v[34:35] op_sel_hi:[1,0,0]
	v_pk_fma_f32 v[160:161], v[28:29], s[14:15], v[34:35] op_sel_hi:[1,0,0]
	v_pk_fma_f32 v[150:151], v[26:27], s[14:15], v[34:35] op_sel_hi:[1,0,0]
	v_pk_fma_f32 v[154:155], v[24:25], s[14:15], v[34:35] op_sel_hi:[1,0,0]
	v_pk_fma_f32 v[158:159], v[22:23], s[14:15], v[34:35] op_sel_hi:[1,0,0]
	v_pk_fma_f32 v[192:193], v[20:21], s[14:15], v[34:35] op_sel_hi:[1,0,0]
	v_pk_fma_f32 v[194:195], v[18:19], s[14:15], v[34:35] op_sel_hi:[1,0,0]
	s_and_b32 s36, s36, 0xffffc000
	v_mov_b64_e32 v[48:49], v[16:17]
	v_mov_b64_e32 v[32:33], v[16:17]
	v_or_b32_e32 v179, s36, v254
	v_mov_b64_e32 v[46:47], v[14:15]
	v_mov_b64_e32 v[44:45], v[12:13]
	v_mov_b64_e32 v[42:43], v[10:11]
	v_mov_b64_e32 v[40:41], v[8:9]
	v_mov_b64_e32 v[38:39], v[6:7]
	v_mov_b64_e32 v[36:37], v[4:5]
	v_mov_b64_e32 v[34:35], v[2:3]
	v_mov_b64_e32 v[30:31], v[14:15]
	v_mov_b64_e32 v[28:29], v[12:13]
	v_mov_b64_e32 v[26:27], v[10:11]
	v_mov_b64_e32 v[24:25], v[8:9]
	v_mov_b64_e32 v[22:23], v[6:7]
	v_mov_b64_e32 v[20:21], v[4:5]
	v_mov_b64_e32 v[18:19], v[2:3]
	v_mul_f32_e32 v190, 0xbe0293ee, v206
	s_mov_b32 s76, 0
	v_readfirstlane_b32 s77, v0
	s_nop 3
	s_lshr_b32 s77, s77, 8
	s_cmp_eq_u32 s77, 0
	s_cbranch_scc1 .Lp5_lead_hi
	s_barrier
	s_branch .Lp5_lead
.Lp5_lead_hi:
	s_setprio 1
